# attention loop step 2: 32-term row sum as 15 v_pk_add_f32 + 1 add (step 1 unchanged)
# baseline (speedup 1.0000x reference)
; #define SB() __builtin_amdgcn_sched_barrier(0)
; #define MF32(a,b,c) __builtin_amdgcn_mfma_f32_32x32x16_bf16(a,b,c,0,0,0)
; #define EXP1(x) x=__builtin_amdgcn_exp2f((x)-mh_)
; __device__ __forceinline__ bf16x8 vfrag(lds_cptr vp,int i){ const s16x4 lo=vtr(vp+(i&3)*4096+(i>>2)*1024), hh=vtr(vp+(i&3)*4096+(i>>2)*1024+512); return (bf16x8){lo[0],lo[1],lo[2],lo[3],hh[0],hh[1],hh[2],hh[3]}; }
; __device__ __forceinline__ u32x4 packw(const f32x16&p,int base){ u32x4 w; w[0]=cvtpk_s(p[base],p[base+1]); w[1]=cvtpk_s(p[base+2],p[base+3]); w[2]=cvtpk_s(p[base+4],p[base+5]); w[3]=cvtpk_s(p[base+6],p[base+7]); return w; }
;   #define KF(i) LDSQ(kpn+((i)>>1)*2048+((i)&1)*512)
;   #define QF(d0) LDSQ(qp+(d0)*1024)
; template<int THRL,bool FIRST> __device__ __forceinline__ void step_main(f32x16&p0,f32x16&p1,f32x16&n0,f32x16&n1,St&S,lds_cptr kpn,lds_cptr qp,lds_cptr vp,float*wsf,int r32,int hi,float&rm){
;     ...
;   bf16x8 ka=KF(0),kb=KF(1),kc=KF(2),kd=KF(3),qa=QF(0),qb=QF(1);
;   decide<THRL,FIRST>(rm,S,wsf,r32,hi);
;   u32x4 pw0,pw1,pw2,pw3; const float mh_=S.mhat; const f32x16 z=f32x16{};
;   SB();
;   n0=MF32(ka,qa,z); ka=KF(4); EXP1(p0[0]);EXP1(p0[1]);EXP1(p0[2]); SB();
;   n1=MF32(kb,qa,z); kb=KF(5); qa=QF(2); EXP1(p0[3]);EXP1(p0[4]);EXP1(p0[5]); SB();
;   n0=MF32(kc,qb,n0);   kc=KF(6); EXP1(p0[6]);EXP1(p0[7]);EXP1(p0[8]); SB();
;   n1=MF32(kd,qb,n1);   kd=KF(7); qb=QF(3); EXP1(p0[9]);EXP1(p0[10]);EXP1(p0[11]); SB();
;   bf16x8 vfa=vfrag(vp,0);
;   n0=MF32(ka,qa,n0);   EXP1(p0[12]);EXP1(p0[13]);EXP1(p0[14]); pw0=packw(p0,0); SB();
;   bf16x8 vfb=vfrag(vp,1);
;   n1=MF32(kb,qa,n1);   EXP1(p0[15]);EXP1(p1[0]);EXP1(p1[1]); SB();
;   bf16x8 vfc=vfrag(vp,2);
;   n0=MF32(kc,qb,n0);   EXP1(p1[2]);EXP1(p1[3]);EXP1(p1[4]); pw1=packw(p0,8); SB();
;   bf16x8 vfd=vfrag(vp,3);
;   n1=MF32(kd,qb,n1);   EXP1(p1[5]);EXP1(p1[6]);EXP1(p1[7]); SB();
;     ...
;   float sa=p0[0]+p0[1];
;     ...
;   PVG(0,pw0,vfa,4, p0[2],p0[3],p0[4],p0[5],   do{EXP1(p1[8]);EXP1(p1[9]);}while(0));
;   PVG(1,pw0,vfb,5, p0[6],p0[7],p0[8],p0[9], do{EXP1(p1[10]);EXP1(p1[11]);}while(0));
;   PVG(2,pw0,vfc,6, p0[10],p0[11],p0[12],p0[13], do{EXP1(p1[12]);EXP1(p1[13]);}while(0));
;   PVG(3,pw0,vfd,7, p0[14],p0[15],p1[0],p1[1],   do{EXP1(p1[14]);EXP1(p1[15]);}while(0));
.LBB0_277:
	s_add_i32 s4, s91, 0x2000
	s_cmpk_lg_i32 s91, 0x4000
	s_cselect_b32 s88, s4, 0
	s_add_i32 s90, s90, 2
	v_mfma_f32_32x32x16_bf16 v[98:113], v[204:207], v[164:167], v[146:161]
	s_add_i32 s4, s88, s84
	s_add_u32 s60, s58, 0xc0000
	s_addc_u32 s61, s59, 0
	s_mov_b32 s5, m0
	s_mov_b32 m0, s4
	s_nop 0
	global_load_lds_dwordx4 v252, s[60:61]
	s_mov_b32 m0, s5
	v_exp_f32_e32 v130, v130
	v_exp_f32_e32 v131, v131
	v_exp_f32_e32 v132, v132
	v_exp_f32_e32 v133, v133
	v_exp_f32_e32 v134, v134
	v_exp_f32_e32 v135, v135
	v_mfma_f32_32x32x16_bf16 v[82:97], v[208:211], v[164:167], v[146:161]
	s_add_u32 s60, s50, 0xc0000
	s_addc_u32 s61, s51, 0
	s_mov_b32 s4, m0
	s_mov_b32 m0, s80
	s_nop 0
	global_load_lds_dwordx4 v250, s[60:61]
	s_mov_b32 m0, s4
	v_mfma_f32_32x32x16_bf16 v[98:113], v[212:215], v[168:171], v[98:113]
	s_add_u32 s60, s50, 0xc0080
	s_addc_u32 s61, s51, 0
	s_mov_b32 s4, m0
	s_mov_b32 m0, s83
	s_nop 0
	global_load_lds_dwordx4 v250, s[60:61]
	s_mov_b32 m0, s4
	v_exp_f32_e32 v136, v136
	v_exp_f32_e32 v137, v137
	v_exp_f32_e32 v138, v138
	v_mfma_f32_32x32x16_bf16 v[82:97], v[216:219], v[168:171], v[82:97]
	v_exp_f32_e32 v139, v139
	v_exp_f32_e32 v140, v140
	v_exp_f32_e32 v141, v141
	v_mfma_f32_32x32x16_bf16 v[98:113], v[220:223], v[172:175], v[98:113]
	v_exp_f32_e32 v142, v142
	ds_read_b64_tr_b16 v[4:5], v246 offset:40960
	ds_read_b64_tr_b16 v[6:7], v246 offset:41472
	v_exp_f32_e32 v143, v143
	v_exp_f32_e32 v144, v144
	v_cvt_pk_bf16_f32 v8, v130, v131
	v_cvt_pk_bf16_f32 v9, v132, v133
	v_cvt_pk_bf16_f32 v10, v134, v135
	v_cvt_pk_bf16_f32 v11, v136, v137
	v_mfma_f32_32x32x16_bf16 v[82:97], v[224:227], v[172:175], v[82:97]
	ds_read_b64_tr_b16 v[178:179], v246 offset:45056
	ds_read_b64_tr_b16 v[180:181], v246 offset:45568
	v_exp_f32_e32 v145, v145
	v_exp_f32_e32 v114, v114
	v_exp_f32_e32 v115, v115
	v_mfma_f32_32x32x16_bf16 v[98:113], v[228:231], v[236:239], v[98:113]
	ds_read_b64_tr_b16 v[182:183], v246 offset:49152
	ds_read_b64_tr_b16 v[184:185], v246 offset:49664
	v_exp_f32_e32 v116, v116
	v_exp_f32_e32 v117, v117
	v_exp_f32_e32 v118, v118
	v_cvt_pk_bf16_f32 v186, v138, v139
	v_cvt_pk_bf16_f32 v187, v140, v141
	v_cvt_pk_bf16_f32 v188, v142, v143
	v_cvt_pk_bf16_f32 v189, v144, v145
	v_mfma_f32_32x32x16_bf16 v[82:97], v[232:235], v[236:239], v[82:97]
	v_add_u32_e32 v240, s91, v249
	ds_read_b64_tr_b16 v[190:191], v246 offset:53248
	ds_read_b64_tr_b16 v[192:193], v246 offset:53760
	v_exp_f32_e32 v119, v119
	v_exp_f32_e32 v120, v120
	v_exp_f32_e32 v121, v121
	s_waitcnt lgkmcnt(6)
	v_mfma_f32_32x32x16_bf16 v[18:33], v[8:11], v[4:7], v[18:33]
	ds_read_b64_tr_b16 v[12:13], v246 offset:41984
	ds_read_b64_tr_b16 v[14:15], v246 offset:42496
	ds_read_b128 v[204:207], v240
	v_exp_f32_e32 v122, v122
	v_exp_f32_e32 v123, v123
	v_pk_add_f32 v[176:177], v[130:131], v[132:133]
	v_pk_add_f32 v[176:177], v[176:177], v[134:135]
	s_waitcnt lgkmcnt(7)
	v_mfma_f32_32x32x16_bf16 v[34:49], v[8:11], v[178:181], v[34:49]
	ds_read_b64_tr_b16 v[4:5], v246 offset:46080
	ds_read_b64_tr_b16 v[6:7], v246 offset:46592
	ds_read_b128 v[208:211], v240 offset:512
	v_exp_f32_e32 v124, v124
	v_exp_f32_e32 v125, v125
	v_pk_add_f32 v[176:177], v[176:177], v[136:137]
	v_pk_add_f32 v[176:177], v[176:177], v[138:139]
	s_waitcnt lgkmcnt(8)
	v_mfma_f32_32x32x16_bf16 v[50:65], v[8:11], v[182:185], v[50:65]
	ds_read_b64_tr_b16 v[178:179], v246 offset:50176
	ds_read_b64_tr_b16 v[180:181], v246 offset:50688
	ds_read_b128 v[212:215], v240 offset:2048
	v_exp_f32_e32 v126, v126
	v_exp_f32_e32 v127, v127
	v_pk_add_f32 v[176:177], v[176:177], v[140:141]
	v_pk_add_f32 v[176:177], v[176:177], v[142:143]
	s_waitcnt lgkmcnt(9)
; __device__ __forceinline__ float max3f(float a,float b,float c){float r;asm("v_max3_f32 %0, %1, %2, %3":"=v"(r):"v"(a),"v"(b),"v"(c));return r;}
; __device__ __forceinline__ float max2f(float a,float b){float r;asm("v_max_f32_e32 %0, %1, %2":"=v"(r):"v"(a),"v"(b));return r;}
; #define EXP1(x) x=__builtin_amdgcn_exp2f((x)-mh_)
;   #define PINAB() asm volatile("":"+v"(ma),"+v"(mb))
; template<int THRL,bool FIRST> __device__ __forceinline__ void step_main(f32x16&p0,f32x16&p1,f32x16&n0,f32x16&n1,St&S,lds_cptr kpn,lds_cptr qp,lds_cptr vp,float*wsf,int r32,int hi,float&rm){
;     ...
;   PVG(0,pw0,vfa,4, p0[2],p0[3],p0[4],p0[5],   do{EXP1(p1[8]);EXP1(p1[9]);}while(0));
;   PVG(1,pw0,vfb,5, p0[6],p0[7],p0[8],p0[9], do{EXP1(p1[10]);EXP1(p1[11]);}while(0));
;   PVG(2,pw0,vfc,6, p0[10],p0[11],p0[12],p0[13], do{EXP1(p1[12]);EXP1(p1[13]);}while(0));
;   PVG(3,pw0,vfd,7, p0[14],p0[15],p1[0],p1[1],   do{EXP1(p1[14]);EXP1(p1[15]);}while(0));
;   PVG(4,pw1,vfa,8, p1[2],p1[3],p1[4],p1[5],   pw2=packw(p1,0));
;   PVG(5,pw1,vfb,9, p1[6],p1[7],p1[8],p1[9], pw3=packw(p1,8));
;   PVG(6,pw1,vfc,10, p1[10],p1[11],p1[12],p1[13], do{}while(0));
;   PVG(7,pw1,vfd,11, p1[14],p1[15],0.f,0.f, do{}while(0));
;   float ma,mb;
;     ...
;   PVG(8,pw2,vfa,12,0.f,0.f,0.f,0.f, do{ma=max3f(n0[0],n0[1],n1[0]);mb=max3f(n0[2],n0[3],n1[1]);PINAB();}while(0));
;   PVG(9,pw2,vfb,13,0.f,0.f,0.f,0.f, do{ma=max3f(ma,n1[2],n1[3]);mb=max3f(mb,n0[4],n0[5]);PINAB();}while(0));
;   PVG(10,pw2,vfc,14,0.f,0.f,0.f,0.f, do{ma=max3f(ma,n0[6],n0[7]);mb=max3f(mb,n1[4],n1[5]);PINAB();}while(0));
;   PVG(11,pw2,vfd,15,0.f,0.f,0.f,0.f, do{ma=max3f(ma,n1[6],n1[7]);mb=max3f(mb,n0[8],n0[9]);PINAB();}while(0));
;   PVG(12,pw3,vfa,16,0.f,0.f,0.f,0.f, do{ma=max3f(ma,n0[10],n0[11]);mb=max3f(mb,n1[8],n1[9]);PINAB();}while(0));
;   PVG(13,pw3,vfb,16,0.f,0.f,0.f,0.f, do{ma=max3f(ma,n1[10],n1[11]);mb=max3f(mb,n0[12],n0[13]);PINAB();}while(0));
;   PVG(14,pw3,vfc,16,0.f,0.f,0.f,0.f, do{ma=max3f(ma,n0[14],n0[15]);mb=max3f(mb,n1[12],n1[13]);PINAB();}while(0));
;   PVG(15,pw3,vfd,16,0.f,0.f,0.f,0.f, do{ma=max3f(ma,n1[14],n1[15]);ma=max2f(ma,mb);PINAB();}while(0));
;     ...
;   { auto rr=__builtin_amdgcn_permlane32_swap(__float_as_uint(ma),__float_as_uint(ma),false,false); rm=max2f(__uint_as_float(rr[0]),__uint_as_float(rr[1])); }
;     ...
;   S.l_reg+=sa;
	v_mfma_f32_32x32x16_bf16 v[66:81], v[8:11], v[190:193], v[66:81]
	ds_read_b64_tr_b16 v[182:183], v246 offset:54272
	ds_read_b64_tr_b16 v[184:185], v246 offset:54784
	ds_read_b128 v[216:219], v240 offset:2560
	v_exp_f32_e32 v128, v128
	v_exp_f32_e32 v129, v129
	v_pk_add_f32 v[176:177], v[176:177], v[144:145]
	v_pk_add_f32 v[176:177], v[176:177], v[114:115]
	s_waitcnt lgkmcnt(10)
	v_mfma_f32_32x32x16_bf16 v[18:33], v[186:189], v[12:15], v[18:33]
	ds_read_b64_tr_b16 v[8:9], v246 offset:43008
	ds_read_b64_tr_b16 v[10:11], v246 offset:43520
	ds_read_b128 v[220:223], v240 offset:4096
	v_pk_add_f32 v[176:177], v[176:177], v[116:117]
	v_pk_add_f32 v[176:177], v[176:177], v[118:119]
	v_cvt_pk_bf16_f32 v12, v114, v115
	v_cvt_pk_bf16_f32 v13, v116, v117
	v_cvt_pk_bf16_f32 v14, v118, v119
	v_cvt_pk_bf16_f32 v15, v120, v121
	s_waitcnt lgkmcnt(10)
	v_mfma_f32_32x32x16_bf16 v[34:49], v[186:189], v[4:7], v[34:49]
	ds_read_b64_tr_b16 v[190:191], v246 offset:47104
	ds_read_b64_tr_b16 v[192:193], v246 offset:47616
	ds_read_b128 v[224:227], v240 offset:4608
	v_pk_add_f32 v[176:177], v[176:177], v[120:121]
	v_pk_add_f32 v[176:177], v[176:177], v[122:123]
	v_cvt_pk_bf16_f32 v4, v122, v123
	v_cvt_pk_bf16_f32 v5, v124, v125
	v_cvt_pk_bf16_f32 v6, v126, v127
	v_cvt_pk_bf16_f32 v7, v128, v129
	s_waitcnt lgkmcnt(10)
	v_mfma_f32_32x32x16_bf16 v[50:65], v[186:189], v[178:181], v[50:65]
	ds_read_b64_tr_b16 v[194:195], v246 offset:51200
	ds_read_b64_tr_b16 v[196:197], v246 offset:51712
	ds_read_b128 v[228:231], v240 offset:6144
	v_pk_add_f32 v[176:177], v[176:177], v[124:125]
	v_pk_add_f32 v[176:177], v[176:177], v[126:127]
	s_waitcnt lgkmcnt(10)
	v_mfma_f32_32x32x16_bf16 v[66:81], v[186:189], v[182:185], v[66:81]
	ds_read_b64_tr_b16 v[178:179], v246 offset:55296
	ds_read_b64_tr_b16 v[180:181], v246 offset:55808
	ds_read_b128 v[232:235], v240 offset:6656
	v_pk_add_f32 v[176:177], v[176:177], v[128:129]
	v_add_f32_e32 v198, v176, v177
	s_waitcnt lgkmcnt(10)
	v_mfma_f32_32x32x16_bf16 v[18:33], v[12:15], v[8:11], v[18:33]
	ds_read_b64_tr_b16 v[182:183], v246 offset:44032
	ds_read_b64_tr_b16 v[184:185], v246 offset:44544
	v_max3_f32 v186, v98, v99, v82
	v_max3_f32 v187, v100, v101, v83
	s_nop 0
	s_waitcnt lgkmcnt(9)
	v_mfma_f32_32x32x16_bf16 v[34:49], v[12:15], v[190:193], v[34:49]
	ds_read_b64_tr_b16 v[8:9], v246 offset:48128
	ds_read_b64_tr_b16 v[10:11], v246 offset:48640
	v_max3_f32 v199, v186, v84, v85
	v_max3_f32 v200, v187, v102, v103
	s_nop 0
	s_waitcnt lgkmcnt(8)
	v_mfma_f32_32x32x16_bf16 v[50:65], v[12:15], v[194:197], v[50:65]
	ds_read_b64_tr_b16 v[186:187], v246 offset:52224
	ds_read_b64_tr_b16 v[188:189], v246 offset:52736
	v_max3_f32 v199, v199, v104, v105
	v_max3_f32 v200, v200, v86, v87
	s_nop 0
	s_waitcnt lgkmcnt(7)
	v_mfma_f32_32x32x16_bf16 v[66:81], v[12:15], v[178:181], v[66:81]
	ds_read_b64_tr_b16 v[190:191], v246 offset:56320
	ds_read_b64_tr_b16 v[192:193], v246 offset:56832
	v_max3_f32 v194, v199, v88, v89
	v_max3_f32 v195, v200, v106, v107
	s_nop 0
	s_waitcnt lgkmcnt(6)
	v_mfma_f32_32x32x16_bf16 v[18:33], v[4:7], v[182:185], v[18:33]
	v_max3_f32 v12, v194, v108, v109
	v_max3_f32 v13, v195, v90, v91
	s_nop 0
	s_waitcnt lgkmcnt(4)
	v_mfma_f32_32x32x16_bf16 v[34:49], v[4:7], v[8:11], v[34:49]
	v_max3_f32 v12, v12, v92, v93
	v_max3_f32 v13, v13, v110, v111
	s_nop 0
	s_waitcnt lgkmcnt(2)
	v_mfma_f32_32x32x16_bf16 v[50:65], v[4:7], v[186:189], v[50:65]
	v_max3_f32 v8, v12, v112, v113
	v_max3_f32 v9, v13, v94, v95
	s_nop 0
	s_waitcnt lgkmcnt(0)
	v_mfma_f32_32x32x16_bf16 v[66:81], v[4:7], v[190:193], v[66:81]
	v_max3_f32 v8, v8, v96, v97
	s_nop 0
	v_max_f32_e32 v8, v8, v9
	s_nop 0
	s_add_u32 s58, s58, 0x180000
	s_addc_u32 s59, s59, 0
	s_add_u32 s50, s50, 0x180000
	s_waitcnt vmcnt(0) lgkmcnt(0)
	s_barrier
	s_addc_u32 s51, s51, 0
	v_mov_b32_e32 v4, v8
	v_add_f32_e32 v251, v17, v198
	s_cmp_lt_u32 s90, s89
	v_permlane32_swap_b32_e32 v8, v4
	v_max_f32_e32 v178, v8, v4
	s_cbranch_scc0 .LBB0_285

; #define SB() __builtin_amdgcn_sched_barrier(0)
; #define MF32(a,b,c) __builtin_amdgcn_mfma_f32_32x32x16_bf16(a,b,c,0,0,0)
; #define EXP1(x) x=__builtin_amdgcn_exp2f((x)-mh_)
; __device__ __forceinline__ bf16x8 vfrag(lds_cptr vp,int i){ const s16x4 lo=vtr(vp+(i&3)*4096+(i>>2)*1024), hh=vtr(vp+(i&3)*4096+(i>>2)*1024+512); return (bf16x8){lo[0],lo[1],lo[2],lo[3],hh[0],hh[1],hh[2],hh[3]}; }
; __device__ __forceinline__ u32x4 packw(const f32x16&p,int base){ u32x4 w; w[0]=cvtpk_s(p[base],p[base+1]); w[1]=cvtpk_s(p[base+2],p[base+3]); w[2]=cvtpk_s(p[base+4],p[base+5]); w[3]=cvtpk_s(p[base+6],p[base+7]); return w; }
;   #define KF(i) LDSQ(kpn+((i)>>1)*2048+((i)&1)*512)
;   #define QF(d0) LDSQ(qp+(d0)*1024)
; template<int THRL,bool FIRST> __device__ __forceinline__ void step_main(f32x16&p0,f32x16&p1,f32x16&n0,f32x16&n1,St&S,lds_cptr kpn,lds_cptr qp,lds_cptr vp,float*wsf,int r32,int hi,float&rm){
;     ...
;   bf16x8 ka=KF(0),kb=KF(1),kc=KF(2),kd=KF(3),qa=QF(0),qb=QF(1);
;   decide<THRL,FIRST>(rm,S,wsf,r32,hi);
;   u32x4 pw0,pw1,pw2,pw3; const float mh_=S.mhat; const f32x16 z=f32x16{};
;   SB();
;   n0=MF32(ka,qa,z); ka=KF(4); EXP1(p0[0]);EXP1(p0[1]);EXP1(p0[2]); SB();
;   n1=MF32(kb,qa,z); kb=KF(5); qa=QF(2); EXP1(p0[3]);EXP1(p0[4]);EXP1(p0[5]); SB();
;   n0=MF32(kc,qb,n0);   kc=KF(6); EXP1(p0[6]);EXP1(p0[7]);EXP1(p0[8]); SB();
;   n1=MF32(kd,qb,n1);   kd=KF(7); qb=QF(3); EXP1(p0[9]);EXP1(p0[10]);EXP1(p0[11]); SB();
;   bf16x8 vfa=vfrag(vp,0);
;   n0=MF32(ka,qa,n0);   EXP1(p0[12]);EXP1(p0[13]);EXP1(p0[14]); pw0=packw(p0,0); SB();
;   bf16x8 vfb=vfrag(vp,1);
;   n1=MF32(kb,qa,n1);   EXP1(p0[15]);EXP1(p1[0]);EXP1(p1[1]); SB();
;   bf16x8 vfc=vfrag(vp,2);
;   n0=MF32(kc,qb,n0);   EXP1(p1[2]);EXP1(p1[3]);EXP1(p1[4]); pw1=packw(p0,8); SB();
;   bf16x8 vfd=vfrag(vp,3);
;   n1=MF32(kd,qb,n1);   EXP1(p1[5]);EXP1(p1[6]);EXP1(p1[7]); SB();
;     ...
;   float sa=p0[0]+p0[1];
;     ...
;   PVG(0,pw0,vfa,4, p0[2],p0[3],p0[4],p0[5],   do{EXP1(p1[8]);EXP1(p1[9]);}while(0));
;   PVG(1,pw0,vfb,5, p0[6],p0[7],p0[8],p0[9], do{EXP1(p1[10]);EXP1(p1[11]);}while(0));
;   PVG(2,pw0,vfc,6, p0[10],p0[11],p0[12],p0[13], do{EXP1(p1[12]);EXP1(p1[13]);}while(0));
;   PVG(3,pw0,vfd,7, p0[14],p0[15],p1[0],p1[1],   do{EXP1(p1[14]);EXP1(p1[15]);}while(0));
.LBB0_435:
	s_add_i32 s4, s89, 0x2000
	s_cmpk_lg_i32 s89, 0x4000
	s_cselect_b32 s86, s4, 0
	s_add_i32 s88, s88, 2
	v_mfma_f32_32x32x16_bf16 v[98:113], v[204:207], v[164:167], v[146:161]
	s_add_i32 s4, s86, s80
	s_add_u32 s58, s50, 0xc0000
	s_addc_u32 s59, s51, 0
	s_mov_b32 s5, m0
	s_mov_b32 m0, s4
	s_nop 0
	global_load_lds_dwordx4 v252, s[58:59]
	s_mov_b32 m0, s5
	v_exp_f32_e32 v130, v130
	v_exp_f32_e32 v131, v131
	v_exp_f32_e32 v132, v132
	v_exp_f32_e32 v133, v133
	v_exp_f32_e32 v134, v134
	v_exp_f32_e32 v135, v135
	v_mfma_f32_32x32x16_bf16 v[82:97], v[208:211], v[164:167], v[146:161]
	s_add_u32 s58, s48, 0xc0000
	s_addc_u32 s59, s49, 0
	s_mov_b32 s4, m0
	s_mov_b32 m0, s78
	s_nop 0
	global_load_lds_dwordx4 v250, s[58:59]
	s_mov_b32 m0, s4
	v_mfma_f32_32x32x16_bf16 v[98:113], v[212:215], v[168:171], v[98:113]
	s_add_u32 s58, s48, 0xc0080
	s_addc_u32 s59, s49, 0
	s_mov_b32 s4, m0
	s_mov_b32 m0, s79
	s_nop 0
	global_load_lds_dwordx4 v250, s[58:59]
	s_mov_b32 m0, s4
	v_exp_f32_e32 v136, v136
	v_exp_f32_e32 v137, v137
	v_exp_f32_e32 v138, v138
	v_mfma_f32_32x32x16_bf16 v[82:97], v[216:219], v[168:171], v[82:97]
	v_exp_f32_e32 v139, v139
	v_exp_f32_e32 v140, v140
	v_exp_f32_e32 v141, v141
	v_mfma_f32_32x32x16_bf16 v[98:113], v[220:223], v[172:175], v[98:113]
	v_exp_f32_e32 v142, v142
	ds_read_b64_tr_b16 v[4:5], v246 offset:40960
	ds_read_b64_tr_b16 v[6:7], v246 offset:41472
	v_exp_f32_e32 v143, v143
	v_exp_f32_e32 v144, v144
	v_cvt_pk_bf16_f32 v8, v130, v131
	v_cvt_pk_bf16_f32 v9, v132, v133
	v_cvt_pk_bf16_f32 v10, v134, v135
	v_cvt_pk_bf16_f32 v11, v136, v137
	v_mfma_f32_32x32x16_bf16 v[82:97], v[224:227], v[172:175], v[82:97]
	ds_read_b64_tr_b16 v[178:179], v246 offset:45056
	ds_read_b64_tr_b16 v[180:181], v246 offset:45568
	v_exp_f32_e32 v145, v145
	v_exp_f32_e32 v114, v114
	v_exp_f32_e32 v115, v115
	v_mfma_f32_32x32x16_bf16 v[98:113], v[228:231], v[236:239], v[98:113]
	ds_read_b64_tr_b16 v[182:183], v246 offset:49152
	ds_read_b64_tr_b16 v[184:185], v246 offset:49664
	v_exp_f32_e32 v116, v116
	v_exp_f32_e32 v117, v117
	v_exp_f32_e32 v118, v118
	v_cvt_pk_bf16_f32 v186, v138, v139
	v_cvt_pk_bf16_f32 v187, v140, v141
	v_cvt_pk_bf16_f32 v188, v142, v143
	v_cvt_pk_bf16_f32 v189, v144, v145
	v_mfma_f32_32x32x16_bf16 v[82:97], v[232:235], v[236:239], v[82:97]
	v_add_u32_e32 v240, s89, v249
	ds_read_b64_tr_b16 v[190:191], v246 offset:53248
	ds_read_b64_tr_b16 v[192:193], v246 offset:53760
	v_exp_f32_e32 v119, v119
	v_exp_f32_e32 v120, v120
	v_exp_f32_e32 v121, v121
	s_waitcnt lgkmcnt(6)
	v_mfma_f32_32x32x16_bf16 v[18:33], v[8:11], v[4:7], v[18:33]
	ds_read_b64_tr_b16 v[12:13], v246 offset:41984
	ds_read_b64_tr_b16 v[14:15], v246 offset:42496
	ds_read_b128 v[204:207], v240
	v_exp_f32_e32 v122, v122
	v_exp_f32_e32 v123, v123
	v_pk_add_f32 v[176:177], v[130:131], v[132:133]
	v_pk_add_f32 v[176:177], v[176:177], v[134:135]
	s_waitcnt lgkmcnt(7)
	v_mfma_f32_32x32x16_bf16 v[34:49], v[8:11], v[178:181], v[34:49]
	ds_read_b64_tr_b16 v[4:5], v246 offset:46080
	ds_read_b64_tr_b16 v[6:7], v246 offset:46592
	ds_read_b128 v[208:211], v240 offset:512
	v_exp_f32_e32 v124, v124
	v_exp_f32_e32 v125, v125
	v_pk_add_f32 v[176:177], v[176:177], v[136:137]
	v_pk_add_f32 v[176:177], v[176:177], v[138:139]
	s_waitcnt lgkmcnt(8)
	v_mfma_f32_32x32x16_bf16 v[50:65], v[8:11], v[182:185], v[50:65]
	ds_read_b64_tr_b16 v[178:179], v246 offset:50176
	ds_read_b64_tr_b16 v[180:181], v246 offset:50688
	ds_read_b128 v[212:215], v240 offset:2048
	v_exp_f32_e32 v126, v126
	v_exp_f32_e32 v127, v127
	v_pk_add_f32 v[176:177], v[176:177], v[140:141]
	v_pk_add_f32 v[176:177], v[176:177], v[142:143]
	s_waitcnt lgkmcnt(9)
; __device__ __forceinline__ float max3f(float a,float b,float c){float r;asm("v_max3_f32 %0, %1, %2, %3":"=v"(r):"v"(a),"v"(b),"v"(c));return r;}
; __device__ __forceinline__ float max2f(float a,float b){float r;asm("v_max_f32_e32 %0, %1, %2":"=v"(r):"v"(a),"v"(b));return r;}
; #define EXP1(x) x=__builtin_amdgcn_exp2f((x)-mh_)
;   #define PINAB() asm volatile("":"+v"(ma),"+v"(mb))
; template<int THRL,bool FIRST> __device__ __forceinline__ void step_main(f32x16&p0,f32x16&p1,f32x16&n0,f32x16&n1,St&S,lds_cptr kpn,lds_cptr qp,lds_cptr vp,float*wsf,int r32,int hi,float&rm){
;     ...
;   PVG(0,pw0,vfa,4, p0[2],p0[3],p0[4],p0[5],   do{EXP1(p1[8]);EXP1(p1[9]);}while(0));
;   PVG(1,pw0,vfb,5, p0[6],p0[7],p0[8],p0[9], do{EXP1(p1[10]);EXP1(p1[11]);}while(0));
;   PVG(2,pw0,vfc,6, p0[10],p0[11],p0[12],p0[13], do{EXP1(p1[12]);EXP1(p1[13]);}while(0));
;   PVG(3,pw0,vfd,7, p0[14],p0[15],p1[0],p1[1],   do{EXP1(p1[14]);EXP1(p1[15]);}while(0));
;   PVG(4,pw1,vfa,8, p1[2],p1[3],p1[4],p1[5],   pw2=packw(p1,0));
;   PVG(5,pw1,vfb,9, p1[6],p1[7],p1[8],p1[9], pw3=packw(p1,8));
;   PVG(6,pw1,vfc,10, p1[10],p1[11],p1[12],p1[13], do{}while(0));
;   PVG(7,pw1,vfd,11, p1[14],p1[15],0.f,0.f, do{}while(0));
;   float ma,mb;
;     ...
;   PVG(8,pw2,vfa,12,0.f,0.f,0.f,0.f, do{ma=max3f(n0[0],n0[1],n1[0]);mb=max3f(n0[2],n0[3],n1[1]);PINAB();}while(0));
;   PVG(9,pw2,vfb,13,0.f,0.f,0.f,0.f, do{ma=max3f(ma,n1[2],n1[3]);mb=max3f(mb,n0[4],n0[5]);PINAB();}while(0));
;   PVG(10,pw2,vfc,14,0.f,0.f,0.f,0.f, do{ma=max3f(ma,n0[6],n0[7]);mb=max3f(mb,n1[4],n1[5]);PINAB();}while(0));
;   PVG(11,pw2,vfd,15,0.f,0.f,0.f,0.f, do{ma=max3f(ma,n1[6],n1[7]);mb=max3f(mb,n0[8],n0[9]);PINAB();}while(0));
;   PVG(12,pw3,vfa,16,0.f,0.f,0.f,0.f, do{ma=max3f(ma,n0[10],n0[11]);mb=max3f(mb,n1[8],n1[9]);PINAB();}while(0));
;   PVG(13,pw3,vfb,16,0.f,0.f,0.f,0.f, do{ma=max3f(ma,n1[10],n1[11]);mb=max3f(mb,n0[12],n0[13]);PINAB();}while(0));
;   PVG(14,pw3,vfc,16,0.f,0.f,0.f,0.f, do{ma=max3f(ma,n0[14],n0[15]);mb=max3f(mb,n1[12],n1[13]);PINAB();}while(0));
;   PVG(15,pw3,vfd,16,0.f,0.f,0.f,0.f, do{ma=max3f(ma,n1[14],n1[15]);ma=max2f(ma,mb);PINAB();}while(0));
;     ...
;   { auto rr=__builtin_amdgcn_permlane32_swap(__float_as_uint(ma),__float_as_uint(ma),false,false); rm=max2f(__uint_as_float(rr[0]),__uint_as_float(rr[1])); }
;     ...
;   S.l_reg+=sa;
	v_mfma_f32_32x32x16_bf16 v[66:81], v[8:11], v[190:193], v[66:81]
	ds_read_b64_tr_b16 v[182:183], v246 offset:54272
	ds_read_b64_tr_b16 v[184:185], v246 offset:54784
	ds_read_b128 v[216:219], v240 offset:2560
	v_exp_f32_e32 v128, v128
	v_exp_f32_e32 v129, v129
	v_pk_add_f32 v[176:177], v[176:177], v[144:145]
	v_pk_add_f32 v[176:177], v[176:177], v[114:115]
	s_waitcnt lgkmcnt(10)
	v_mfma_f32_32x32x16_bf16 v[18:33], v[186:189], v[12:15], v[18:33]
	ds_read_b64_tr_b16 v[8:9], v246 offset:43008
	ds_read_b64_tr_b16 v[10:11], v246 offset:43520
	ds_read_b128 v[220:223], v240 offset:4096
	v_pk_add_f32 v[176:177], v[176:177], v[116:117]
	v_pk_add_f32 v[176:177], v[176:177], v[118:119]
	v_cvt_pk_bf16_f32 v12, v114, v115
	v_cvt_pk_bf16_f32 v13, v116, v117
	v_cvt_pk_bf16_f32 v14, v118, v119
	v_cvt_pk_bf16_f32 v15, v120, v121
	s_waitcnt lgkmcnt(10)
	v_mfma_f32_32x32x16_bf16 v[34:49], v[186:189], v[4:7], v[34:49]
	ds_read_b64_tr_b16 v[190:191], v246 offset:47104
	ds_read_b64_tr_b16 v[192:193], v246 offset:47616
	ds_read_b128 v[224:227], v240 offset:4608
	v_pk_add_f32 v[176:177], v[176:177], v[120:121]
	v_pk_add_f32 v[176:177], v[176:177], v[122:123]
	v_cvt_pk_bf16_f32 v4, v122, v123
	v_cvt_pk_bf16_f32 v5, v124, v125
	v_cvt_pk_bf16_f32 v6, v126, v127
	v_cvt_pk_bf16_f32 v7, v128, v129
	s_waitcnt lgkmcnt(10)
	v_mfma_f32_32x32x16_bf16 v[50:65], v[186:189], v[178:181], v[50:65]
	ds_read_b64_tr_b16 v[194:195], v246 offset:51200
	ds_read_b64_tr_b16 v[196:197], v246 offset:51712
	ds_read_b128 v[228:231], v240 offset:6144
	v_pk_add_f32 v[176:177], v[176:177], v[124:125]
	v_pk_add_f32 v[176:177], v[176:177], v[126:127]
	s_waitcnt lgkmcnt(10)
	v_mfma_f32_32x32x16_bf16 v[66:81], v[186:189], v[182:185], v[66:81]
	ds_read_b64_tr_b16 v[178:179], v246 offset:55296
	ds_read_b64_tr_b16 v[180:181], v246 offset:55808
	ds_read_b128 v[232:235], v240 offset:6656
	v_pk_add_f32 v[176:177], v[176:177], v[128:129]
	v_add_f32_e32 v198, v176, v177
	s_waitcnt lgkmcnt(10)
	v_mfma_f32_32x32x16_bf16 v[18:33], v[12:15], v[8:11], v[18:33]
	ds_read_b64_tr_b16 v[182:183], v246 offset:44032
	ds_read_b64_tr_b16 v[184:185], v246 offset:44544
	v_max3_f32 v186, v98, v99, v82
	v_max3_f32 v187, v100, v101, v83
	s_nop 0
	s_waitcnt lgkmcnt(9)
	v_mfma_f32_32x32x16_bf16 v[34:49], v[12:15], v[190:193], v[34:49]
	ds_read_b64_tr_b16 v[8:9], v246 offset:48128
	ds_read_b64_tr_b16 v[10:11], v246 offset:48640
	v_max3_f32 v199, v186, v84, v85
	v_max3_f32 v200, v187, v102, v103
	s_nop 0
	s_waitcnt lgkmcnt(8)
	v_mfma_f32_32x32x16_bf16 v[50:65], v[12:15], v[194:197], v[50:65]
	ds_read_b64_tr_b16 v[186:187], v246 offset:52224
	ds_read_b64_tr_b16 v[188:189], v246 offset:52736
	v_max3_f32 v199, v199, v104, v105
	v_max3_f32 v200, v200, v86, v87
	s_nop 0
	s_waitcnt lgkmcnt(7)
	v_mfma_f32_32x32x16_bf16 v[66:81], v[12:15], v[178:181], v[66:81]
	ds_read_b64_tr_b16 v[190:191], v246 offset:56320
	ds_read_b64_tr_b16 v[192:193], v246 offset:56832
	v_max3_f32 v194, v199, v88, v89
	v_max3_f32 v195, v200, v106, v107
	s_nop 0
	s_waitcnt lgkmcnt(6)
	v_mfma_f32_32x32x16_bf16 v[18:33], v[4:7], v[182:185], v[18:33]
	v_max3_f32 v12, v194, v108, v109
	v_max3_f32 v13, v195, v90, v91
	s_nop 0
	s_waitcnt lgkmcnt(4)
	v_mfma_f32_32x32x16_bf16 v[34:49], v[4:7], v[8:11], v[34:49]
	v_max3_f32 v12, v12, v92, v93
	v_max3_f32 v13, v13, v110, v111
	s_nop 0
	s_waitcnt lgkmcnt(2)
	v_mfma_f32_32x32x16_bf16 v[50:65], v[4:7], v[186:189], v[50:65]
	v_max3_f32 v8, v12, v112, v113
	v_max3_f32 v9, v13, v94, v95
	s_nop 0
	s_waitcnt lgkmcnt(0)
	v_mfma_f32_32x32x16_bf16 v[66:81], v[4:7], v[190:193], v[66:81]
	v_max3_f32 v8, v8, v96, v97
	s_nop 0
	v_max_f32_e32 v8, v8, v9
	s_nop 0
	s_add_u32 s50, s50, 0x180000
	s_addc_u32 s51, s51, 0
	s_add_u32 s48, s48, 0x180000
	s_waitcnt vmcnt(0) lgkmcnt(0)
	s_barrier
	s_addc_u32 s49, s49, 0
	v_mov_b32_e32 v4, v8
	v_add_f32_e32 v251, v17, v198
	s_cmp_lt_u32 s88, s87
	v_permlane32_swap_b32_e32 v8, v4
	v_max_f32_e32 v178, v8, v4
	s_cbranch_scc0 .LBB0_443
